# speedup vs baseline: 1.0007x; 1.0007x over previous
.LBB0_64:
	s_lshl_b32 s0, s33, 3
	v_readlane_b32 s1, v242, 1
	s_waitcnt lgkmcnt(0)
	s_add_i32 s12, s0, s1
	s_cmpk_gt_u32 s12, 0x1fff
	v_mbcnt_lo_u32_b32 v0, -1, 0
	v_mbcnt_hi_u32_b32 v0, -1, v0
	s_cbranch_scc1 .LBB0_73
	s_add_u32 s2, s4, s91
	s_addc_u32 s3, s5, 0
	s_lshl_b32 s16, s84, 3
	s_lshl_b32 s0, s12, 13
	v_and_b32_e32 v36, 63, v0
	s_add_u32 s0, s2, s0
	v_mov_b32_e32 v65, 0
	s_addc_u32 s1, s3, 0
	v_lshlrev_b32_e32 v64, 5, v36
	v_lshl_add_u64 v[24:25], s[0:1], 0, v[64:65]
	s_movk_i32 s17, 0x1000
	global_load_dwordx4 v[0:3], v64, s[0:1] offset:16 nt
	global_load_dwordx4 v[4:7], v64, s[0:1] nt
	global_load_dwordx4 v[8:11], v64, s[0:1] offset:2064 nt
	global_load_dwordx4 v[12:15], v64, s[0:1] offset:2048 nt
	s_mov_b64 s[4:5], 0x1000
	v_add_co_u32_e32 v32, vcc, s17, v24
	v_lshl_add_u64 v[26:27], v[24:25], 0, s[4:5]
	s_nop 0
	v_addc_co_u32_e32 v33, vcc, 0, v25, vcc
	s_mov_b64 s[6:7], 0x1800
	global_load_dwordx4 v[16:19], v[32:33], off nt
	global_load_dwordx4 v[20:23], v[26:27], off offset:16 nt
	v_lshl_add_u64 v[34:35], v[24:25], 0, s[6:7]
	global_load_dwordx4 v[24:27], v[32:33], off offset:2048 nt
	global_load_dwordx4 v[28:31], v[34:35], off offset:16 nt
	v_lshlrev_b32_e32 v32, 3, v36
	v_lshl_add_u64 v[66:67], s[2:3], 0, v[64:65]
	v_lshlrev_b32_e32 v64, 4, v36
	v_lshl_add_u64 v[68:69], s[54:55], 0, v[64:65]
	v_lshlrev_b32_e32 v64, 2, v32
	v_mbcnt_lo_u32_b32 v32, -1, 0
	v_mbcnt_hi_u32_b32 v70, -1, v32
	v_and_b32_e32 v32, 64, v70
	s_mov_b32 s11, 0
	v_cmp_eq_u32_e64 s[0:1], 0, v36
	s_lshl_b32 s18, s84, 4
	v_add_u32_e32 v71, 64, v32
	v_xor_b32_e32 v72, 32, v70
	v_xor_b32_e32 v73, 16, v70
	v_xor_b32_e32 v74, 8, v70
	v_xor_b32_e32 v75, 4, v70
	v_xor_b32_e32 v76, 2, v70
	v_xor_b32_e32 v77, 1, v70
	v_mov_b32_e32 v78, 0x358637bd
	s_mov_b32 s19, 0x800000
	s_waitcnt vmcnt(0)
	s_branch .LBB0_67

.LBB0_67:
	s_add_i32 s10, s12, s16
	s_lshl_b64 s[14:15], s[10:11], 13
	v_lshl_add_u64 v[32:33], v[66:67], 0, s[14:15]
	s_add_u32 s14, s2, s14
	s_addc_u32 s15, s3, s15
	global_load_dwordx4 v[48:51], v[32:33], off offset:16 nt
	global_load_dwordx4 v[60:63], v[32:33], off nt
	v_lshl_add_u64 v[32:33], s[14:15], 0, v[64:65]
	v_add_co_u32_e32 v80, vcc, s17, v32
	v_lshl_add_u64 v[34:35], v[32:33], 0, s[4:5]
	s_nop 0
	v_addc_co_u32_e32 v81, vcc, 0, v33, vcc
	s_waitcnt lgkmcnt(0)
	global_load_dwordx4 v[36:39], v64, s[14:15] offset:2064 nt
	global_load_dwordx4 v[52:55], v64, s[14:15] offset:2048 nt
	global_load_dwordx4 v[56:59], v[80:81], off nt
	global_load_dwordx4 v[44:47], v[34:35], off offset:16 nt
	v_lshl_add_u64 v[82:83], v[32:33], 0, s[6:7]
	global_load_dwordx4 v[40:43], v[80:81], off offset:2048 nt
	global_load_dwordx4 v[32:35], v[82:83], off offset:16 nt
	s_waitcnt vmcnt(19)
	v_mul_f32_e32 v80, v5, v5
	v_fmac_f32_e32 v80, v4, v4
	v_fmac_f32_e32 v80, v6, v6
	v_fmac_f32_e32 v80, v7, v7
	v_fmac_f32_e32 v80, v0, v0
	v_fmac_f32_e32 v80, v1, v1
	v_fmac_f32_e32 v80, v2, v2
	v_fmac_f32_e32 v80, v3, v3
	s_waitcnt vmcnt(17)
	v_fmac_f32_e32 v80, v12, v12
	v_fmac_f32_e32 v80, v13, v13
	v_fmac_f32_e32 v80, v14, v14
	v_fmac_f32_e32 v80, v15, v15
	v_fmac_f32_e32 v80, v8, v8
	v_fmac_f32_e32 v80, v9, v9
	v_fmac_f32_e32 v80, v10, v10
	v_fmac_f32_e32 v80, v11, v11
	s_waitcnt vmcnt(16)
	v_fmac_f32_e32 v80, v16, v16
	v_fmac_f32_e32 v80, v17, v17
	v_fmac_f32_e32 v80, v18, v18
	v_fmac_f32_e32 v80, v19, v19
	s_waitcnt vmcnt(15)
	v_fmac_f32_e32 v80, v20, v20
	v_fmac_f32_e32 v80, v21, v21
	v_fmac_f32_e32 v80, v22, v22
	v_fmac_f32_e32 v80, v23, v23
	s_waitcnt vmcnt(14)
	v_fmac_f32_e32 v80, v24, v24
	v_fmac_f32_e32 v80, v25, v25
	v_fmac_f32_e32 v80, v26, v26
	v_fmac_f32_e32 v80, v27, v27
	s_waitcnt vmcnt(13)
	v_fmac_f32_e32 v80, v28, v28
	v_fmac_f32_e32 v80, v29, v29
	v_cmp_lt_i32_e32 vcc, v72, v71
	v_fmac_f32_e32 v80, v30, v30
	v_fmac_f32_e32 v80, v31, v31
	v_cndmask_b32_e32 v79, v70, v72, vcc
	v_lshlrev_b32_e32 v79, 2, v79
	ds_bpermute_b32 v81, v79, v80
	v_cmp_lt_i32_e32 vcc, v73, v71
	s_mov_b32 s13, s11
	s_lshl_b64 s[14:15], s[12:13], 12
	v_cvt_pk_bf16_f32 v82, v4, v5
	s_waitcnt lgkmcnt(0)
	v_add_f32_e32 v81, v80, v81
	v_cndmask_b32_e32 v80, v70, v73, vcc
	v_lshlrev_b32_e32 v80, 2, v80
	ds_bpermute_b32 v86, v80, v81
	v_cmp_lt_i32_e32 vcc, v74, v71
	v_lshl_add_u64 v[92:93], v[68:69], 0, s[14:15]
	v_cvt_pk_bf16_f32 v83, v6, v7
	v_cvt_pk_bf16_f32 v84, v0, v1
	s_waitcnt lgkmcnt(0)
	v_add_f32_e32 v87, v81, v86
	v_cndmask_b32_e32 v81, v70, v74, vcc
	v_lshlrev_b32_e32 v81, 2, v81
	ds_bpermute_b32 v88, v81, v87
	v_cmp_lt_i32_e32 vcc, v75, v71
	v_cvt_pk_bf16_f32 v85, v2, v3
	global_store_dwordx4 v[92:93], v[82:85], off nt
	v_cvt_pk_bf16_f32 v86, v8, v9
	v_cvt_pk_bf16_f32 v91, v30, v31
	s_nop 1
	v_cndmask_b32_e32 v82, v70, v75, vcc
	s_waitcnt lgkmcnt(0)
	v_add_f32_e32 v83, v87, v88
	v_lshlrev_b32_e32 v82, 2, v82
	ds_bpermute_b32 v88, v82, v83
	v_cmp_lt_i32_e32 vcc, v76, v71
	v_cvt_pk_bf16_f32 v84, v12, v13
	v_cvt_pk_bf16_f32 v85, v14, v15
	v_cvt_pk_bf16_f32 v87, v10, v11
	s_waitcnt lgkmcnt(0)
	v_add_f32_e32 v89, v83, v88
	global_store_dwordx4 v[92:93], v[84:87], off offset:1024 nt
	v_cndmask_b32_e32 v83, v70, v76, vcc
	v_lshlrev_b32_e32 v83, 2, v83
	ds_bpermute_b32 v90, v83, v89
	v_cvt_pk_bf16_f32 v84, v16, v17
	v_cmp_lt_i32_e32 vcc, v77, v71
	v_cvt_pk_bf16_f32 v85, v18, v19
	v_cvt_pk_bf16_f32 v86, v20, v21
	v_cvt_pk_bf16_f32 v87, v22, v23
	global_store_dwordx4 v[92:93], v[84:87], off offset:2048 nt
	v_cvt_pk_bf16_f32 v88, v24, v25
	s_nop 1
	v_cndmask_b32_e32 v84, v70, v77, vcc
	s_waitcnt lgkmcnt(0)
	v_add_f32_e32 v85, v89, v90
	v_lshlrev_b32_e32 v84, 2, v84
	ds_bpermute_b32 v86, v84, v85
	v_cvt_pk_bf16_f32 v89, v26, v27
	v_cvt_pk_bf16_f32 v90, v28, v29
	global_store_dwordx4 v[92:93], v[88:91], off offset:3072 nt
	s_and_saveexec_b64 s[14:15], s[0:1]
	s_cbranch_execz .LBB0_69
	s_waitcnt lgkmcnt(0)
	v_add_f32_e32 v85, v85, v86
	v_fmamk_f32 v85, v85, 0x3a000000, v78
	v_mul_f32_e32 v86, 0x4b800000, v85
	v_cmp_gt_f32_e32 vcc, s19, v85
	s_lshl_b64 s[20:21], s[12:13], 2
	s_add_u32 s20, s87, s20
	v_cndmask_b32_e32 v85, v85, v86, vcc
	v_rsq_f32_e32 v85, v85
	s_addc_u32 s21, s88, s21
	v_mul_f32_e32 v86, 0x45800000, v85
	v_cndmask_b32_e32 v85, v85, v86, vcc
	global_store_dword v65, v85, s[20:21]

.LBB0_71:
	s_waitcnt vmcnt(19)
	v_mul_f32_e32 v85, v61, v61
	v_fmac_f32_e32 v85, v60, v60
	v_fmac_f32_e32 v85, v62, v62
	v_fmac_f32_e32 v85, v63, v63
	v_fmac_f32_e32 v85, v48, v48
	v_fmac_f32_e32 v85, v49, v49
	v_fmac_f32_e32 v85, v50, v50
	v_fmac_f32_e32 v85, v51, v51
	s_waitcnt vmcnt(17)
	v_fmac_f32_e32 v85, v52, v52
	v_fmac_f32_e32 v85, v53, v53
	v_fmac_f32_e32 v85, v54, v54
	v_fmac_f32_e32 v85, v55, v55
	v_fmac_f32_e32 v85, v36, v36
	v_fmac_f32_e32 v85, v37, v37
	v_fmac_f32_e32 v85, v38, v38
	v_fmac_f32_e32 v85, v39, v39
	s_waitcnt vmcnt(16)
	v_fmac_f32_e32 v85, v56, v56
	v_fmac_f32_e32 v85, v57, v57
	v_fmac_f32_e32 v85, v58, v58
	v_fmac_f32_e32 v85, v59, v59
	s_waitcnt vmcnt(15)
	v_fmac_f32_e32 v85, v44, v44
	v_fmac_f32_e32 v85, v45, v45
	v_fmac_f32_e32 v85, v46, v46
	v_fmac_f32_e32 v85, v47, v47
	s_waitcnt vmcnt(14)
	v_fmac_f32_e32 v85, v40, v40
	v_fmac_f32_e32 v85, v41, v41
	v_fmac_f32_e32 v85, v42, v42
	v_fmac_f32_e32 v85, v43, v43
	s_waitcnt vmcnt(13)
	v_fmac_f32_e32 v85, v32, v32
	v_fmac_f32_e32 v85, v33, v33
	v_fmac_f32_e32 v85, v34, v34
	v_fmac_f32_e32 v85, v35, v35
	ds_bpermute_b32 v79, v79, v85
	v_cvt_pk_bf16_f32 v60, v60, v61
	v_cvt_pk_bf16_f32 v61, v62, v63
	v_cvt_pk_bf16_f32 v63, v50, v51
	v_cvt_pk_bf16_f32 v62, v48, v49
	s_waitcnt lgkmcnt(0)
	v_add_f32_e32 v79, v85, v79
	ds_bpermute_b32 v80, v80, v79
	v_cvt_pk_bf16_f32 v48, v52, v53
	s_lshl_b64 s[12:13], s[10:11], 12
	v_lshl_add_u64 v[86:87], v[68:69], 0, s[12:13]
	v_cvt_pk_bf16_f32 v49, v54, v55
	s_waitcnt lgkmcnt(0)
	v_add_f32_e32 v51, v79, v80
	ds_bpermute_b32 v79, v81, v51
	v_cvt_pk_bf16_f32 v50, v36, v37
	v_cvt_pk_bf16_f32 v36, v56, v57
	v_cvt_pk_bf16_f32 v37, v58, v59
	global_store_dwordx4 v[86:87], v[60:63], off nt
	s_waitcnt lgkmcnt(0)
	v_add_f32_e32 v52, v51, v79
	ds_bpermute_b32 v53, v82, v52
	v_cvt_pk_bf16_f32 v51, v38, v39
	global_store_dwordx4 v[86:87], v[48:51], off offset:1024 nt
	v_cvt_pk_bf16_f32 v38, v44, v45
	v_cvt_pk_bf16_f32 v39, v46, v47
	global_store_dwordx4 v[86:87], v[36:39], off offset:2048 nt
	s_waitcnt lgkmcnt(0)
	v_add_f32_e32 v48, v52, v53
	ds_bpermute_b32 v49, v83, v48
	v_cvt_pk_bf16_f32 v38, v40, v41
	v_cvt_pk_bf16_f32 v39, v42, v43
	v_cvt_pk_bf16_f32 v40, v32, v33
	v_cvt_pk_bf16_f32 v41, v34, v35
	s_waitcnt lgkmcnt(0)
	v_add_f32_e32 v36, v48, v49
	ds_bpermute_b32 v37, v84, v36
	global_store_dwordx4 v[86:87], v[38:41], off offset:3072 nt
	s_and_saveexec_b64 s[12:13], s[0:1]
	s_cbranch_execz .LBB0_66
	s_waitcnt lgkmcnt(0)
	v_add_f32_e32 v32, v36, v37
	v_fmamk_f32 v32, v32, 0x3a000000, v78
	v_mul_f32_e32 v33, 0x4b800000, v32
	v_cmp_gt_f32_e32 vcc, s19, v32
	s_lshl_b64 s[14:15], s[10:11], 2
	s_add_u32 s14, s87, s14
	v_cndmask_b32_e32 v32, v32, v33, vcc
	v_rsq_f32_e32 v32, v32
	s_addc_u32 s15, s88, s15
	v_mul_f32_e32 v33, 0x45800000, v32
	v_cndmask_b32_e32 v32, v32, v33, vcc
	global_store_dword v65, v32, s[14:15]
	s_branch .LBB0_66
.Lr0_last:
	s_waitcnt vmcnt(0)
	s_branch .LBB0_71

.LBB0_194:
	s_add_u32 s40, s48, s91
	s_addc_u32 s41, s49, 0
	s_cmp_lt_i32 s52, 5
	s_cselect_b64 s[0:1], -1, 0
	s_cmp_gt_i32 s53, 4
	s_cselect_b64 s[2:3], -1, 0
	s_and_b64 s[0:1], s[0:1], s[2:3]
	s_andn2_b64 vcc, exec, s[0:1]
	s_cbranch_vccnz .LBB0_218
	s_lshl_b32 s0, s33, 3
	v_readlane_b32 s1, v242, 1
	s_waitcnt lgkmcnt(0)
	s_add_i32 s8, s0, s1
	s_cmpk_gt_u32 s8, 0x1fff
	v_mbcnt_lo_u32_b32 v0, -1, 0
	v_mbcnt_hi_u32_b32 v0, -1, v0
	s_cbranch_scc1 .LBB0_208
	v_and_b32_e32 v64, 63, v0
	v_lshlrev_b32_e32 v96, 5, v64
	v_mov_b32_e32 v97, 0
	s_add_u32 s0, s54, 0x8000000
	s_waitcnt vmcnt(0)
	v_lshl_add_u64 v[24:25], s[38:39], 0, v[96:97]
	s_mov_b64 s[2:3], 0x1000
	s_addc_u32 s1, s55, 0
	v_lshl_add_u64 v[26:27], v[24:25], 0, s[2:3]
	s_mov_b64 s[2:3], 0x1800
	s_lshl_b32 s12, s84, 3
	s_lshl_b32 s4, s8, 12
	v_lshl_add_u64 v[34:35], v[24:25], 0, s[2:3]
	s_add_u32 s2, s54, s4
	v_add_co_u32_e32 v32, vcc, 0x1000, v24
	s_addc_u32 s3, s55, 0
	global_load_dwordx4 v[0:3], v96, s[38:39]
	global_load_dwordx4 v[4:7], v96, s[38:39] offset:16
	global_load_dwordx4 v[8:11], v96, s[38:39] offset:2048
	global_load_dwordx4 v[12:15], v96, s[38:39] offset:2064
	v_addc_co_u32_e32 v33, vcc, 0, v25, vcc
	v_lshlrev_b32_e32 v96, 4, v64
	s_add_u32 s4, s0, s4
	global_load_dwordx4 v[16:19], v[32:33], off
	global_load_dwordx4 v[20:23], v[26:27], off offset:16
	s_nop 0
	global_load_dwordx4 v[24:27], v[32:33], off offset:2048
	global_load_dwordx4 v[28:31], v[34:35], off offset:16
	s_addc_u32 s5, s1, 0
	global_load_dwordx4 v[32:35], v96, s[2:3] nt
	global_load_dwordx4 v[36:39], v96, s[2:3] offset:1024 nt
	global_load_dwordx4 v[40:43], v96, s[4:5] nt
	global_load_dwordx4 v[44:47], v96, s[4:5] offset:1024 nt
	global_load_dwordx4 v[48:51], v96, s[2:3] offset:2048 nt
	global_load_dwordx4 v[52:55], v96, s[2:3] offset:3072 nt
	global_load_dwordx4 v[56:59], v96, s[4:5] offset:2048 nt
	global_load_dwordx4 v[60:63], v96, s[4:5] offset:3072 nt
	v_lshl_add_u64 v[100:101], s[0:1], 0, v[96:97]
	v_cmp_eq_u32_e64 s[0:1], 0, v64
	v_mbcnt_lo_u32_b32 v64, -1, 0
	v_mbcnt_hi_u32_b32 v64, -1, v64
	v_and_b32_e32 v65, 64, v64
	v_add_u32_e32 v65, 64, v65
	v_xor_b32_e32 v66, 32, v64
	v_cmp_lt_i32_e32 vcc, v66, v65
	v_lshl_add_u64 v[98:99], s[54:55], 0, v[96:97]
	v_lshl_add_u64 v[102:103], s[40:41], 0, v[96:97]
	v_cndmask_b32_e32 v66, v64, v66, vcc
	v_lshlrev_b32_e32 v96, 2, v66
	v_xor_b32_e32 v66, 16, v64
	v_cmp_lt_i32_e32 vcc, v66, v65
	s_cmp_lg_u64 s[48:49], 0
	s_cselect_b64 s[2:3], -1, 0
	v_cndmask_b32_e32 v66, v64, v66, vcc
	v_lshlrev_b32_e32 v104, 2, v66
	v_xor_b32_e32 v66, 8, v64
	v_cmp_lt_i32_e32 vcc, v66, v65
	s_mov_b32 s5, 0
	s_lshl_b32 s13, s84, 4
	v_cndmask_b32_e32 v66, v64, v66, vcc
	v_lshlrev_b32_e32 v105, 2, v66
	v_xor_b32_e32 v66, 4, v64
	v_cmp_lt_i32_e32 vcc, v66, v65
	v_mov_b32_e32 v109, 0x358637bd
	s_mov_b32 s14, 0x800000
	v_cndmask_b32_e32 v66, v64, v66, vcc
	v_lshlrev_b32_e32 v106, 2, v66
	v_xor_b32_e32 v66, 2, v64
	v_cmp_lt_i32_e32 vcc, v66, v65
	s_nop 1
	v_cndmask_b32_e32 v66, v64, v66, vcc
	v_lshlrev_b32_e32 v107, 2, v66
	v_xor_b32_e32 v66, 1, v64
	v_cmp_lt_i32_e32 vcc, v66, v65
	s_nop 1
	v_cndmask_b32_e32 v64, v64, v66, vcc
	v_lshlrev_b32_e32 v108, 2, v64
	v_cndmask_b32_e64 v64, 0, 1, s[2:3]
	v_cmp_ne_u32_e64 s[2:3], 1, v64
	s_waitcnt vmcnt(0)
	s_branch .LBB0_198

.LBB0_198:
	s_waitcnt vmcnt(10)
	v_and_b32_e32 v147, 0xffff0000, v40
	v_lshlrev_b32_e32 v146, 16, v40
	v_mul_f32_e32 v115, v147, v147
	v_lshlrev_b32_e32 v148, 16, v41
	v_fmac_f32_e32 v115, v146, v146
	v_and_b32_e32 v149, 0xffff0000, v41
	v_fmac_f32_e32 v115, v148, v148
	v_lshlrev_b32_e32 v150, 16, v42
	v_fmac_f32_e32 v115, v149, v149
	v_and_b32_e32 v151, 0xffff0000, v42
	v_fmac_f32_e32 v115, v150, v150
	v_lshlrev_b32_e32 v152, 16, v43
	v_fmac_f32_e32 v115, v151, v151
	v_and_b32_e32 v153, 0xffff0000, v43
	v_fmac_f32_e32 v115, v152, v152
	v_fmac_f32_e32 v115, v153, v153
	s_waitcnt vmcnt(9)
	v_lshlrev_b32_e32 v154, 16, v44
	v_and_b32_e32 v155, 0xffff0000, v44
	v_fmac_f32_e32 v115, v154, v154
	v_lshlrev_b32_e32 v156, 16, v45
	v_fmac_f32_e32 v115, v155, v155
	v_and_b32_e32 v157, 0xffff0000, v45
	v_fmac_f32_e32 v115, v156, v156
	v_lshlrev_b32_e32 v158, 16, v46
	v_fmac_f32_e32 v115, v157, v157
	v_and_b32_e32 v159, 0xffff0000, v46
	v_fmac_f32_e32 v115, v158, v158
	v_lshlrev_b32_e32 v160, 16, v47
	v_fmac_f32_e32 v115, v159, v159
	v_and_b32_e32 v161, 0xffff0000, v47
	v_fmac_f32_e32 v115, v160, v160
	v_fmac_f32_e32 v115, v161, v161
	s_waitcnt vmcnt(6)
	v_lshlrev_b32_e32 v162, 16, v56
	v_and_b32_e32 v163, 0xffff0000, v56
	v_fmac_f32_e32 v115, v162, v162
	s_add_i32 s4, s8, s12
	v_lshlrev_b32_e32 v164, 16, v57
	v_fmac_f32_e32 v115, v163, v163
	s_lshl_b64 s[6:7], s[4:5], 12
	v_and_b32_e32 v165, 0xffff0000, v57
	v_fmac_f32_e32 v115, v164, v164
	v_lshl_add_u64 v[110:111], v[98:99], 0, s[6:7]
	v_lshlrev_b32_e32 v166, 16, v58
	v_fmac_f32_e32 v115, v165, v165
	v_lshl_add_u64 v[112:113], v[100:101], 0, s[6:7]
	global_load_dwordx4 v[76:79], v[110:111], off nt
	global_load_dwordx4 v[72:75], v[110:111], off offset:1024 nt
	global_load_dwordx4 v[92:95], v[112:113], off nt
	global_load_dwordx4 v[88:91], v[112:113], off offset:1024 nt
	global_load_dwordx4 v[68:71], v[110:111], off offset:2048 nt
	s_waitcnt lgkmcnt(0)
	global_load_dwordx4 v[64:67], v[110:111], off offset:3072 nt
	global_load_dwordx4 v[84:87], v[112:113], off offset:2048 nt
	global_load_dwordx4 v[80:83], v[112:113], off offset:3072 nt
	v_and_b32_e32 v167, 0xffff0000, v58
	v_fmac_f32_e32 v115, v166, v166
	v_lshlrev_b32_e32 v168, 16, v59
	v_fmac_f32_e32 v115, v167, v167
	v_and_b32_e32 v169, 0xffff0000, v59
	v_fmac_f32_e32 v115, v168, v168
	v_fmac_f32_e32 v115, v169, v169
	s_waitcnt vmcnt(13)
	v_lshlrev_b32_e32 v170, 16, v60
	v_and_b32_e32 v171, 0xffff0000, v60
	v_fmac_f32_e32 v115, v170, v170
	v_lshlrev_b32_e32 v172, 16, v61
	v_fmac_f32_e32 v115, v171, v171
	v_and_b32_e32 v173, 0xffff0000, v61
	v_fmac_f32_e32 v115, v172, v172
	v_and_b32_e32 v142, 0xffff0000, v62
	v_lshlrev_b32_e32 v143, 16, v62
	v_fmac_f32_e32 v115, v173, v173
	v_pk_mul_f32 v[116:117], v[142:143], v[142:143]
	v_and_b32_e32 v144, 0xffff0000, v63
	v_add_f32_e32 v115, v117, v115
	v_lshlrev_b32_e32 v145, 16, v63
	v_add_f32_e32 v115, v116, v115
	v_pk_mul_f32 v[116:117], v[144:145], v[144:145]
	v_lshlrev_b32_e32 v112, 16, v32
	v_add_f32_e32 v115, v117, v115
	v_add_f32_e32 v115, v116, v115
	ds_bpermute_b32 v116, v96, v115
	v_and_b32_e32 v114, 0xffff0000, v32
	v_lshlrev_b32_e32 v113, 16, v33
	v_and_b32_e32 v111, 0xffff0000, v33
	v_lshlrev_b32_e32 v110, 16, v34
	s_waitcnt lgkmcnt(0)
	v_add_f32_e32 v115, v115, v116
	ds_bpermute_b32 v116, v104, v115
	v_and_b32_e32 v141, 0xffff0000, v34
	v_lshlrev_b32_e32 v140, 16, v35
	v_and_b32_e32 v138, 0xffff0000, v35
	v_lshlrev_b32_e32 v136, 16, v36
	s_waitcnt lgkmcnt(0)
	v_add_f32_e32 v115, v115, v116
	ds_bpermute_b32 v116, v105, v115
	v_and_b32_e32 v139, 0xffff0000, v36
	v_lshlrev_b32_e32 v137, 16, v37
	v_and_b32_e32 v134, 0xffff0000, v37
	v_lshlrev_b32_e32 v132, 16, v38
	s_waitcnt lgkmcnt(0)
	v_add_f32_e32 v115, v115, v116
	ds_bpermute_b32 v116, v106, v115
	v_and_b32_e32 v135, 0xffff0000, v38
	v_lshlrev_b32_e32 v133, 16, v39
	v_and_b32_e32 v130, 0xffff0000, v39
	v_lshlrev_b32_e32 v127, 16, v48
	s_waitcnt lgkmcnt(0)
	v_add_f32_e32 v115, v115, v116
	ds_bpermute_b32 v116, v107, v115
	v_and_b32_e32 v131, 0xffff0000, v48
	v_lshlrev_b32_e32 v128, 16, v49
	v_and_b32_e32 v124, 0xffff0000, v49
	v_lshlrev_b32_e32 v121, 16, v50
	s_waitcnt lgkmcnt(0)
	v_add_f32_e32 v123, v115, v116
	ds_bpermute_b32 v126, v108, v123
	v_and_b32_e32 v125, 0xffff0000, v50
	v_lshlrev_b32_e32 v122, 16, v51
	v_and_b32_e32 v119, 0xffff0000, v51
	v_lshlrev_b32_e32 v117, 16, v52
	s_waitcnt lgkmcnt(0)
	v_add_f32_e32 v123, v123, v126
	v_fmamk_f32 v123, v123, 0x3a000000, v109
	v_mul_f32_e32 v126, 0x4b800000, v123
	v_cmp_gt_f32_e32 vcc, s14, v123
	v_and_b32_e32 v120, 0xffff0000, v52
	v_and_b32_e32 v129, 0xffff0000, v54
	v_cndmask_b32_e32 v123, v123, v126, vcc
	v_rsq_f32_e32 v174, v123
	v_lshlrev_b32_e32 v118, 16, v53
	v_lshlrev_b32_e32 v126, 16, v55
	v_and_b32_e32 v116, 0xffff0000, v53
	v_mul_f32_e32 v175, 0x45800000, v174
	v_cndmask_b32_e32 v174, v174, v175, vcc
	v_mul_f32_e32 v146, v174, v146
	v_fmac_f32_e32 v112, v0, v146
	v_mul_f32_e32 v146, v174, v147
	v_fmac_f32_e32 v114, v1, v146
	v_mul_f32_e32 v146, v174, v148
	v_fmac_f32_e32 v113, v2, v146
	v_mul_f32_e32 v146, v174, v149
	v_fmac_f32_e32 v111, v3, v146
	v_mul_f32_e32 v146, v174, v150
	v_fmac_f32_e32 v110, v4, v146
	v_mul_f32_e32 v146, v174, v151
	v_fmac_f32_e32 v141, v5, v146
	v_mul_f32_e32 v146, v174, v152
	v_fmac_f32_e32 v140, v6, v146
	v_mul_f32_e32 v146, v174, v153
	v_fmac_f32_e32 v138, v7, v146
	v_mul_f32_e32 v146, v174, v154
	v_fmac_f32_e32 v136, v8, v146
	v_mul_f32_e32 v146, v174, v155
	v_fmac_f32_e32 v139, v9, v146
	v_mul_f32_e32 v146, v174, v156
	v_fmac_f32_e32 v137, v10, v146
	v_mul_f32_e32 v146, v174, v157
	v_fmac_f32_e32 v134, v11, v146
	v_mul_f32_e32 v146, v174, v158
	v_fmac_f32_e32 v132, v12, v146
	v_mul_f32_e32 v146, v174, v159
	v_fmac_f32_e32 v135, v13, v146
	v_mul_f32_e32 v146, v174, v160
	v_fmac_f32_e32 v133, v14, v146
	v_mul_f32_e32 v146, v174, v161
	v_fmac_f32_e32 v130, v15, v146
	v_mul_f32_e32 v146, v174, v162
	v_fmac_f32_e32 v127, v16, v146
	v_mul_f32_e32 v146, v174, v163
	v_fmac_f32_e32 v131, v17, v146
	v_mul_f32_e32 v146, v174, v164
	v_fmac_f32_e32 v128, v18, v146
	v_mul_f32_e32 v146, v174, v165
	v_fmac_f32_e32 v124, v19, v146
	v_mul_f32_e32 v146, v174, v166
	v_fmac_f32_e32 v121, v20, v146
	v_mul_f32_e32 v146, v174, v167
	v_fmac_f32_e32 v125, v21, v146
	v_mul_f32_e32 v146, v174, v168
	v_fmac_f32_e32 v122, v22, v146
	v_mul_f32_e32 v146, v174, v169
	v_fmac_f32_e32 v119, v23, v146
	v_mul_f32_e32 v146, v174, v170
	v_fmac_f32_e32 v117, v24, v146
	v_mul_f32_e32 v146, v174, v171
	v_mul_f32_e32 v142, v174, v142
	v_fmac_f32_e32 v120, v25, v146
	v_mul_f32_e32 v146, v174, v172
	v_fmac_f32_e32 v129, v29, v142
	v_mul_f32_e32 v142, v174, v145
	v_lshlrev_b32_e32 v115, 16, v54
	v_and_b32_e32 v123, 0xffff0000, v55
	v_fmac_f32_e32 v118, v26, v146
	v_mul_f32_e32 v146, v174, v173
	v_mul_f32_e32 v143, v174, v143
	v_fmac_f32_e32 v126, v30, v142
	v_mul_f32_e32 v142, v174, v144
	v_fmac_f32_e32 v116, v27, v146
	v_fmac_f32_e32 v115, v28, v143
	s_and_b64 vcc, exec, s[2:3]
	v_fmac_f32_e32 v123, v31, v142
	s_cbranch_vccnz .LBB0_200
	s_mov_b32 s9, s5
	s_lshl_b64 s[10:11], s[8:9], 13
	v_cvt_pk_bf16_f32 v142, v112, v114
	v_cvt_pk_bf16_f32 v143, v113, v111
	v_cvt_pk_bf16_f32 v144, v110, v141
	v_cvt_pk_bf16_f32 v145, v140, v138
	v_lshl_add_u64 v[146:147], v[102:103], 0, s[10:11]
	global_store_dwordx4 v[146:147], v[142:145], off nt
	s_nop 1
	v_cvt_pk_bf16_f32 v142, v136, v139
	v_cvt_pk_bf16_f32 v143, v137, v134
	v_cvt_pk_bf16_f32 v144, v132, v135
	v_cvt_pk_bf16_f32 v145, v133, v130
	global_store_dwordx4 v[146:147], v[142:145], off offset:1024 nt
	s_nop 1
	v_cvt_pk_bf16_f32 v142, v127, v131
	v_cvt_pk_bf16_f32 v143, v128, v124
	v_cvt_pk_bf16_f32 v144, v121, v125
	v_cvt_pk_bf16_f32 v145, v122, v119
	global_store_dwordx4 v[146:147], v[142:145], off offset:2048 nt
	s_nop 1
	v_cvt_pk_bf16_f32 v142, v117, v120
	v_cvt_pk_bf16_f32 v143, v118, v116
	v_cvt_pk_bf16_f32 v144, v115, v129
	v_cvt_pk_bf16_f32 v145, v126, v123
	global_store_dwordx4 v[146:147], v[142:145], off offset:3072 nt

.LBB0_204:
	s_waitcnt vmcnt(18)
	v_and_b32_e32 v116, 0xffff0000, v92
	v_lshlrev_b32_e32 v113, 16, v92
	v_mul_f32_e32 v92, v116, v116
	v_lshlrev_b32_e32 v117, 16, v93
	v_fmac_f32_e32 v92, v113, v113
	v_and_b32_e32 v118, 0xffff0000, v93
	v_fmac_f32_e32 v92, v117, v117
	v_lshlrev_b32_e32 v119, 16, v94
	v_fmac_f32_e32 v92, v118, v118
	v_and_b32_e32 v120, 0xffff0000, v94
	v_fmac_f32_e32 v92, v119, v119
	v_lshlrev_b32_e32 v121, 16, v95
	v_fmac_f32_e32 v92, v120, v120
	v_and_b32_e32 v122, 0xffff0000, v95
	v_fmac_f32_e32 v92, v121, v121
	v_fmac_f32_e32 v92, v122, v122
	s_waitcnt vmcnt(17)
	v_lshlrev_b32_e32 v123, 16, v88
	v_and_b32_e32 v124, 0xffff0000, v88
	v_fmac_f32_e32 v92, v123, v123
	v_lshlrev_b32_e32 v125, 16, v89
	v_fmac_f32_e32 v92, v124, v124
	v_and_b32_e32 v126, 0xffff0000, v89
	v_fmac_f32_e32 v92, v125, v125
	v_lshlrev_b32_e32 v127, 16, v90
	v_fmac_f32_e32 v92, v126, v126
	v_and_b32_e32 v128, 0xffff0000, v90
	v_fmac_f32_e32 v92, v127, v127
	v_lshlrev_b32_e32 v129, 16, v91
	v_fmac_f32_e32 v92, v128, v128
	v_and_b32_e32 v130, 0xffff0000, v91
	v_fmac_f32_e32 v92, v129, v129
	v_fmac_f32_e32 v92, v130, v130
	s_waitcnt vmcnt(14)
	v_lshlrev_b32_e32 v131, 16, v84
	v_and_b32_e32 v132, 0xffff0000, v84
	v_fmac_f32_e32 v92, v131, v131
	v_lshlrev_b32_e32 v133, 16, v85
	v_fmac_f32_e32 v92, v132, v132
	v_and_b32_e32 v134, 0xffff0000, v85
	v_fmac_f32_e32 v92, v133, v133
	v_lshlrev_b32_e32 v135, 16, v86
	v_fmac_f32_e32 v92, v134, v134
	v_and_b32_e32 v136, 0xffff0000, v86
	v_fmac_f32_e32 v92, v135, v135
	v_lshlrev_b32_e32 v137, 16, v87
	v_fmac_f32_e32 v92, v136, v136
	v_and_b32_e32 v138, 0xffff0000, v87
	v_fmac_f32_e32 v92, v137, v137
	v_fmac_f32_e32 v92, v138, v138
	s_waitcnt vmcnt(13)
	v_lshlrev_b32_e32 v139, 16, v80
	v_and_b32_e32 v140, 0xffff0000, v80
	v_fmac_f32_e32 v92, v139, v139
	v_lshlrev_b32_e32 v141, 16, v81
	v_fmac_f32_e32 v92, v140, v140
	v_and_b32_e32 v142, 0xffff0000, v81
	v_fmac_f32_e32 v92, v141, v141
	v_and_b32_e32 v94, 0xffff0000, v82
	v_lshlrev_b32_e32 v95, 16, v82
	v_fmac_f32_e32 v92, v142, v142
	v_pk_mul_f32 v[80:81], v[94:95], v[94:95]
	v_and_b32_e32 v114, 0xffff0000, v83
	v_add_f32_e32 v81, v81, v92
	v_lshlrev_b32_e32 v115, 16, v83
	v_add_f32_e32 v82, v80, v81
	v_pk_mul_f32 v[80:81], v[114:115], v[114:115]
	v_lshlrev_b32_e32 v110, 16, v76
	v_add_f32_e32 v81, v81, v82
	v_add_f32_e32 v80, v80, v81
	ds_bpermute_b32 v81, v96, v80
	v_and_b32_e32 v112, 0xffff0000, v76
	v_lshlrev_b32_e32 v76, 16, v78
	v_and_b32_e32 v93, 0xffff0000, v78
	v_lshlrev_b32_e32 v92, 16, v79
	s_waitcnt lgkmcnt(0)
	v_add_f32_e32 v78, v80, v81
	v_and_b32_e32 v90, 0xffff0000, v79
	ds_bpermute_b32 v79, v104, v78
	v_lshlrev_b32_e32 v88, 16, v72
	v_and_b32_e32 v91, 0xffff0000, v72
	v_lshlrev_b32_e32 v89, 16, v73
	v_and_b32_e32 v86, 0xffff0000, v73
	s_waitcnt lgkmcnt(0)
	v_add_f32_e32 v72, v78, v79
	ds_bpermute_b32 v73, v105, v72
	v_lshlrev_b32_e32 v85, 16, v75
	v_and_b32_e32 v82, 0xffff0000, v75
	v_lshlrev_b32_e32 v84, 16, v74
	v_and_b32_e32 v87, 0xffff0000, v74
	s_waitcnt lgkmcnt(0)
	v_add_f32_e32 v73, v72, v73
	ds_bpermute_b32 v75, v106, v73
	v_lshlrev_b32_e32 v80, 16, v69
	v_and_b32_e32 v74, 0xffff0000, v69
	v_lshlrev_b32_e32 v79, 16, v68
	v_and_b32_e32 v83, 0xffff0000, v68
	s_waitcnt lgkmcnt(0)
	v_add_f32_e32 v69, v73, v75
	ds_bpermute_b32 v78, v107, v69
	v_lshlrev_b32_e32 v72, 16, v70
	v_and_b32_e32 v75, 0xffff0000, v70
	v_lshlrev_b32_e32 v73, 16, v71
	v_and_b32_e32 v70, 0xffff0000, v71
	s_waitcnt lgkmcnt(0)
	v_add_f32_e32 v78, v69, v78
	ds_bpermute_b32 v81, v108, v78
	v_lshlrev_b32_e32 v68, 16, v64
	v_and_b32_e32 v71, 0xffff0000, v64
	v_lshlrev_b32_e32 v64, 16, v66
	v_lshlrev_b32_e32 v111, 16, v77
	s_waitcnt lgkmcnt(0)
	v_add_f32_e32 v78, v78, v81
	v_fmamk_f32 v78, v78, 0x3a000000, v109
	v_mul_f32_e32 v81, 0x4b800000, v78
	v_cmp_gt_f32_e32 vcc, s14, v78
	v_and_b32_e32 v77, 0xffff0000, v77
	v_lshlrev_b32_e32 v69, 16, v65
	v_cndmask_b32_e32 v78, v78, v81, vcc
	v_rsq_f32_e32 v143, v78
	v_and_b32_e32 v81, 0xffff0000, v66
	v_lshlrev_b32_e32 v78, 16, v67
	v_and_b32_e32 v66, 0xffff0000, v67
	v_mul_f32_e32 v67, 0x45800000, v143
	v_cndmask_b32_e32 v67, v143, v67, vcc
	v_mul_f32_e32 v113, v67, v113
	v_fmac_f32_e32 v110, v0, v113
	v_mul_f32_e32 v113, v67, v116
	v_fmac_f32_e32 v112, v1, v113
	v_mul_f32_e32 v113, v67, v117
	v_fmac_f32_e32 v111, v2, v113
	v_mul_f32_e32 v113, v67, v118
	v_fmac_f32_e32 v77, v3, v113
	v_mul_f32_e32 v113, v67, v119
	v_fmac_f32_e32 v76, v4, v113
	v_mul_f32_e32 v113, v67, v120
	v_fmac_f32_e32 v93, v5, v113
	v_mul_f32_e32 v113, v67, v121
	v_fmac_f32_e32 v92, v6, v113
	v_mul_f32_e32 v113, v67, v122
	v_fmac_f32_e32 v90, v7, v113
	v_mul_f32_e32 v113, v67, v123
	v_fmac_f32_e32 v88, v8, v113
	v_mul_f32_e32 v113, v67, v124
	v_fmac_f32_e32 v91, v9, v113
	v_mul_f32_e32 v113, v67, v125
	v_fmac_f32_e32 v89, v10, v113
	v_mul_f32_e32 v113, v67, v126
	v_fmac_f32_e32 v86, v11, v113
	v_mul_f32_e32 v113, v67, v127
	v_fmac_f32_e32 v84, v12, v113
	v_mul_f32_e32 v113, v67, v128
	v_fmac_f32_e32 v87, v13, v113
	v_mul_f32_e32 v113, v67, v129
	v_fmac_f32_e32 v85, v14, v113
	v_mul_f32_e32 v113, v67, v130
	v_fmac_f32_e32 v82, v15, v113
	v_mul_f32_e32 v113, v67, v131
	v_fmac_f32_e32 v79, v16, v113
	v_mul_f32_e32 v113, v67, v132
	v_fmac_f32_e32 v83, v17, v113
	v_mul_f32_e32 v113, v67, v133
	v_fmac_f32_e32 v80, v18, v113
	v_mul_f32_e32 v113, v67, v134
	v_fmac_f32_e32 v74, v19, v113
	v_mul_f32_e32 v113, v67, v135
	v_fmac_f32_e32 v72, v20, v113
	v_mul_f32_e32 v113, v67, v136
	v_fmac_f32_e32 v75, v21, v113
	v_mul_f32_e32 v113, v67, v137
	v_fmac_f32_e32 v73, v22, v113
	v_mul_f32_e32 v113, v67, v138
	v_fmac_f32_e32 v70, v23, v113
	v_mul_f32_e32 v113, v67, v139
	v_fmac_f32_e32 v68, v24, v113
	v_mul_f32_e32 v113, v67, v140
	v_fmac_f32_e32 v71, v25, v113
	v_mul_f32_e32 v113, v67, v141
	v_mul_f32_e32 v94, v67, v94
	v_and_b32_e32 v65, 0xffff0000, v65
	v_fmac_f32_e32 v69, v26, v113
	v_mul_f32_e32 v113, v67, v142
	v_mul_f32_e32 v95, v67, v95
	v_fmac_f32_e32 v81, v29, v94
	v_mul_f32_e32 v94, v67, v115
	v_mul_f32_e32 v67, v67, v114
	v_fmac_f32_e32 v65, v27, v113
	v_fmac_f32_e32 v64, v28, v95
	v_fmac_f32_e32 v78, v30, v94
	s_and_b64 vcc, exec, s[2:3]
	v_fmac_f32_e32 v66, v31, v67
	s_cbranch_vccnz .LBB0_206
	v_cvt_pk_bf16_f32 v114, v110, v112
	v_cvt_pk_bf16_f32 v115, v111, v77
	v_cvt_pk_bf16_f32 v116, v76, v93
	v_cvt_pk_bf16_f32 v117, v92, v90
	v_lshl_add_u64 v[94:95], s[6:7], 1, v[102:103]
	global_store_dwordx4 v[94:95], v[114:117], off nt
	s_nop 1
	v_cvt_pk_bf16_f32 v114, v88, v91
	v_cvt_pk_bf16_f32 v115, v89, v86
	v_cvt_pk_bf16_f32 v116, v84, v87
	v_cvt_pk_bf16_f32 v117, v85, v82
	global_store_dwordx4 v[94:95], v[114:117], off offset:1024 nt
	s_nop 1
	v_cvt_pk_bf16_f32 v114, v79, v83
	v_cvt_pk_bf16_f32 v115, v80, v74
	v_cvt_pk_bf16_f32 v116, v72, v75
	v_cvt_pk_bf16_f32 v117, v73, v70
	global_store_dwordx4 v[94:95], v[114:117], off offset:2048 nt
	s_nop 1
	v_cvt_pk_bf16_f32 v114, v68, v71
	v_cvt_pk_bf16_f32 v115, v69, v65
	v_cvt_pk_bf16_f32 v116, v64, v81
	v_cvt_pk_bf16_f32 v117, v78, v66
	global_store_dwordx4 v[94:95], v[114:117], off offset:3072 nt
